# scan loader: counted vmcnt waits (W1 vmcnt(8) except last iter, W2 vmcnt(6)), baseline compute loop
# speedup vs baseline: 1.0003x; 1.0003x over previous
; __device__ __forceinline__ unsigned xb_ld(unsigned* p)              { return __hip_atomic_load(p, __ATOMIC_RELAXED, __HIP_MEMORY_SCOPE_AGENT); }
; #define SC_LOAD(Q, c) do { const size_t o_ = offA + (size_t)(c) * SC_TC * DR; (Q).r = *(const u32x2*)(P.SR + o_); (Q).k = *(const u32x2*)(P.SKT + o_); (Q).wr = *(const u32x2*)(P.SWR + o_); \
;         (Q).m = *(const u32x2*)(P.SREM + o_); (Q).d = *(const u32x2*)(lbase + (size_t)(c) * SC_TC * 3072); if (isv) (Q).v = *(const u32x2*)(P.SV + o_); } while (0)
; __device__ __forceinline__ void scan_item(LAS unsigned char* lds, const ScanPtrs& P, bf16* YC, int item, unsigned* half_cnt, unsigned half_expect) {
;     ...
;         SC_LOAD(q0, 0); SC_LOAD(q1, 1); SC_STORE(q0, 0); SC_LOAD(q0, 2);
;         __syncthreads();
;         for (int c = 0; c < NCH; c += 2) {
;             if (c == NCH / 4 - 8) {
;                 unsigned sp_ = 0u; while (xb_ld(half_cnt) < half_expect) { __builtin_amdgcn_s_sleep(8); if (++sp_ > (1u << 20)) break; }
;                 __builtin_amdgcn_fence(__ATOMIC_ACQUIRE, "agent"); asm volatile("s_waitcnt vmcnt(0)" ::: "memory"); }
;             SC_STORE(q1, 1); if (c + 3 < NCH) SC_LOAD(q1, c + 3);
.LBB0_757:
	s_cmpk_lt_u32 s25, 0xfe
	s_cbranch_scc1 .Lldr_w1_relaxed
	s_waitcnt vmcnt(2)
	s_branch .Lldr_w1_done
.Lldr_w1_relaxed:
	s_waitcnt vmcnt(8)
.Lldr_w1_done:
	v_cvt_f32_f16_e32 v6, v37
	v_cvt_f32_f16_e32 v11, v36
	v_cvt_f32_f16_sdwa v63, v37 dst_sel:DWORD dst_unused:UNUSED_PAD src0_sel:WORD_1
	v_cvt_f32_f16_sdwa v65, v36 dst_sel:DWORD dst_unused:UNUSED_PAD src0_sel:WORD_1
	v_sub_f32_e32 v66, 1.0, v6
	v_sub_f32_e32 v64, 1.0, v11
	v_sub_f32_e32 v67, 1.0, v63
	v_sub_f32_e32 v65, 1.0, v65
	ds_write_b128 v52, v[64:67] offset:22528
	v_lshlrev_b32_e32 v64, 16, v32
	v_and_b32_e32 v65, 0xffff0000, v32
	v_lshlrev_b32_e32 v66, 16, v33
	v_and_b32_e32 v67, 0xffff0000, v33
	ds_write_b128 v52, v[64:67] offset:22784
	v_lshlrev_b32_e32 v64, 16, v30
	v_and_b32_e32 v65, 0xffff0000, v30
	v_lshlrev_b32_e32 v66, 16, v31
	v_and_b32_e32 v67, 0xffff0000, v31
	ds_write_b128 v52, v[64:67] offset:23040
	v_lshlrev_b32_e32 v64, 16, v28
	v_and_b32_e32 v65, 0xffff0000, v28
	v_lshlrev_b32_e32 v66, 16, v29
	v_and_b32_e32 v67, 0xffff0000, v29
	ds_write_b128 v52, v[64:67] offset:23296
	v_lshlrev_b32_e32 v64, 16, v26
	v_and_b32_e32 v65, 0xffff0000, v26
	v_lshlrev_b32_e32 v66, 16, v27
	v_and_b32_e32 v67, 0xffff0000, v27
	ds_write_b128 v52, v[64:67] offset:23552
	s_and_saveexec_b64 s[16:17], s[2:3]
	s_cbranch_execnz .LBB0_768
	s_or_b64 exec, exec, s[16:17]
	s_cmpk_gt_u32 s25, 0xfc
	s_cbranch_scc0 .LBB0_769
